# combo12: combo11 + early L2 writeback issued by the first workgroup of each XCD to arrive at a barrier (the last arriver's writeback then finds less dirty data)
# baseline (speedup 1.0000x reference)
; __device__ __forceinline__ unsigned xb_add(unsigned* p, unsigned v) { return __hip_atomic_fetch_add(p, v, __ATOMIC_RELAXED, __HIP_MEMORY_SCOPE_AGENT); }
; __device__ __forceinline__ void xcd_barrier(const XcdBarrier& b) {
;     ...
;         const unsigned old = xb_add(&bar[XB_XSUB(bx)], 1u);
;         const unsigned gen = old / nloc;
;         if (old + 1u == (gen + 1u) * nloc) {
;             __builtin_amdgcn_fence(__ATOMIC_RELEASE, "agent");
;             asm volatile("s_waitcnt vmcnt(0)" ::: "memory");
.Lxbg_b:
	s_add_i32 s12, s13, s18
	s_cmp_eq_u32 s12, s21
	s_cbranch_scc0 .Lxbg_nf
	buffer_wbl2 sc1

; __device__ __forceinline__ unsigned xb_add(unsigned* p, unsigned v) { return __hip_atomic_fetch_add(p, v, __ATOMIC_RELAXED, __HIP_MEMORY_SCOPE_AGENT); }
; __device__ __forceinline__ void xcd_barrier(const XcdBarrier& b) {
;     ...
;         const unsigned old = xb_add(&bar[XB_XSUB(bx)], 1u);
;         const unsigned gen = old / nloc;
;         if (old + 1u == (gen + 1u) * nloc) {
;             __builtin_amdgcn_fence(__ATOMIC_RELEASE, "agent");
;             asm volatile("s_waitcnt vmcnt(0)" ::: "memory");
.Lxb0_b:
	s_add_i32 s12, s13, s18
	s_cmp_eq_u32 s12, s3
	s_cbranch_scc0 .Lxb0_nf
	buffer_wbl2 sc1
